# P0: fifth-round weight-transpose items moved from the GEMV workgroups 0..63 to workgroups 192..255
# speedup vs baseline: 1.0020x; 1.0015x over previous
.LBB0_15:
	s_add_i32 s26, s26, s6
	s_add_i32 s7, s7, s10
	s_add_i32 s11, s11, s24
	s_cmpk_lt_i32 s26, 0x2000
	s_cbranch_scc1 .LBB0_16
	s_add_i32 s99, s4, 0x2000
	s_cmp_lg_u32 s26, s99
	s_cbranch_scc1 .LBB0_36
	s_cmpk_lt_u32 s4, 0x600
	s_cbranch_scc1 .LBB0_36
	s_add_i32 s26, s4, 0x1a00
	s_lshl_b32 s7, s26, 5
	s_lshl_b32 s11, s26, 1
	s_add_i32 s11, s11, 0x1cc00
